# static pair assignment in prep_segment (no atomic fetch, no loop-top barrier) + wave0 latency fix
# speedup vs baseline: 1.0009x; 1.0009x over previous
.LBB0_264:
	v_mov_b32_e32 v0, v228
	s_mov_b32 s0, 0x12000
	v_ashrrev_i32_e32 v147, 8, v0
	v_mad_i32_i24 v146, v147, s0, 0
	v_and_b32_e32 v156, 0xff, v0
	v_cmp_eq_u32_e64 s[42:43], 0, v0
	v_add_u32_e32 v157, 0x11800, v146
	v_add_u32_e32 v158, 0x119fc, v146
	v_add_u32_e32 v159, 0x11900, v146
	s_mov_b32 s0, 0
	v_writelane_b32 v255, s0, 17
	s_branch .LBB0_267

.LBB0_267:
	v_readlane_b32 s0, v255, 17
	v_readlane_b32 s2, v250, 0
	s_nop 3
	s_add_i32 s1, s0, 1
	v_writelane_b32 v255, s1, 17
	s_cmp_lt_u32 s0, 1
	v_mov_b32_e32 v0, s2
	s_mov_b64 s[0:1], -1
	s_cbranch_scc0 .LBB0_266
	v_lshl_add_u32 v0, v0, 1, v147
	v_ashrrev_i32_e32 v2, 31, v0
	v_lshrrev_b32_e32 v2, 30, v2
	v_add_u32_e32 v2, v0, v2
	v_ashrrev_i32_e32 v162, 2, v2
	v_and_b32_e32 v2, -4, v2
	v_sub_u32_e32 v161, v0, v2
	v_and_b32_e32 v164, 1, v162
	v_lshlrev_b32_e32 v2, 4, v162
	v_sub_u32_e32 v0, 3, v161
	v_cmp_eq_u32_e64 s[44:45], 0, v164
	v_and_b32_e32 v2, 0xffffff00, v2
	v_mov_b32_e32 v148, v156
	v_cndmask_b32_e64 v0, v0, v161, s[44:45]
	v_add_u32_e32 v26, 0x8000, v2
	v_bfe_u32 v163, v162, 1, 3
	v_ashrrev_i32_e32 v27, 31, v26
	v_lshlrev_b32_e32 v4, 6, v0
	v_cmp_gt_u32_e64 s[46:47], 64, v148
	v_bfrev_b32_e32 v165, 1
	v_lshl_or_b32 v130, v164, 3, v163
	v_lshlrev_b32_e32 v130, 2, v130
	s_nop 0
	v_readfirstlane_b32 s100, v130
	s_nop 4
	s_load_dword s101, s[82:83], s100
	s_load_dword s100, s[80:81], s100
	v_mov_b32_e32 v130, 0
	v_mov_b32_e32 v166, 0
	s_and_saveexec_b64 s[0:1], s[46:47]
	s_cbranch_execz .LBB0_274
	v_xor_b32_e32 v0, 63, v148
	v_ashrrev_i32_e32 v5, 31, v4
	v_cndmask_b32_e64 v0, v0, v148, s[44:45]
	v_lshl_add_u64 v[2:3], v[4:5], 0, v[26:27]
	v_or_b32_e32 v2, v2, v0
	v_readlane_b32 s22, v251, 58
	v_lshlrev_b64 v[2:3], 7, v[2:3]
	v_readlane_b32 s23, v251, 59
	v_lshlrev_b32_e32 v0, 5, v164
	s_nop 0
	v_lshl_add_u64 v[2:3], s[22:23], 0, v[2:3]
	v_lshl_add_u64 v[2:3], v[2:3], 0, v[0:1]
	v_lshlrev_b32_e32 v0, 2, v163
	v_lshl_add_u64 v[2:3], v[2:3], 0, v[0:1]
	global_load_dword v165, v[2:3], off
	global_load_dword v166, v[2:3], off offset:64

.LBB0_547:
	v_readlane_b32 s0, v254, 47
	v_readlane_b32 s1, v254, 48
	s_andn2_b64 vcc, exec, s[0:1]
	s_cbranch_vccnz .LBB0_620
	v_mov_b32_e32 v0, v228
	s_mov_b32 s0, 0x12000
	v_ashrrev_i32_e32 v147, 8, v0
	v_mad_i32_i24 v146, v147, s0, 0
	v_and_b32_e32 v156, 0xff, v0
	v_cmp_eq_u32_e64 s[42:43], 0, v0
	v_add_u32_e32 v157, 0x11800, v146
	v_add_u32_e32 v158, 0x119fc, v146
	v_add_u32_e32 v159, 0x11900, v146
	s_mov_b32 s0, 0
	v_writelane_b32 v255, s0, 17
	s_branch .LBB0_551

.LBB0_551:
	v_readlane_b32 s0, v255, 17
	v_readlane_b32 s2, v250, 0
	s_nop 3
	s_add_i32 s1, s0, 1
	v_writelane_b32 v255, s1, 17
	s_cmp_lt_u32 s2, 0x80
	s_cbranch_scc1 .Lps_b
	s_lshl_b32 s1, s0, 7
	s_add_i32 s1, s1, s2
	s_addk_i32 s1, 0xff80
	s_cmp_lt_u32 s0, 3
	s_branch .Lps_j
.Lps_b:
	s_add_i32 s1, s2, 0x180
	s_cmp_lt_u32 s0, 1
.Lps_j:
	v_mov_b32_e32 v0, s1
	s_mov_b64 s[0:1], -1
	s_cbranch_scc0 .LBB0_550
	v_lshl_add_u32 v0, v0, 1, v147
	v_sub_u32_e32 v3, 0, v0
	v_max_i32_e32 v3, v0, v3
	v_mul_hi_u32 v4, v3, v247
	v_mul_lo_u32 v5, v4, s17
	v_sub_u32_e32 v3, v3, v5
	v_add_u32_e32 v5, 1, v4
	v_cmp_le_u32_e32 vcc, s17, v3
	v_ashrrev_i32_e32 v2, 31, v0
	v_readlane_b32 s0, v254, 33
	v_cndmask_b32_e32 v4, v4, v5, vcc
	v_subrev_u32_e32 v5, s17, v3
	v_cndmask_b32_e32 v3, v3, v5, vcc
	v_add_u32_e32 v5, 1, v4
	v_cmp_le_u32_e32 vcc, s17, v3
	v_mov_b32_e32 v148, v156
	v_bfrev_b32_e32 v165, 1
	v_cndmask_b32_e32 v3, v4, v5, vcc
	v_xor_b32_e32 v3, v3, v2
	v_sub_u32_e32 v162, v3, v2
	v_mul_lo_u32 v2, v162, s17
	v_sub_u32_e32 v161, v0, v2
	v_and_b32_e32 v164, 1, v162
	v_add_u32_e32 v2, s0, v161
	v_ashrrev_i32_e32 v0, 4, v162
	v_sub_u32_e32 v3, s36, v2
	v_cmp_eq_u32_e64 s[44:45], 0, v164
	v_readlane_b32 s0, v254, 31
	v_readlane_b32 s1, v254, 32
	v_cndmask_b32_e64 v2, v3, v2, s[44:45]
	v_lshl_add_u32 v3, v0, 8, v246
	v_lshlrev_b32_e32 v0, 12, v0
	v_cndmask_b32_e64 v26, v0, v3, s[0:1]
	v_bfe_u32 v163, v162, 1, 3
	v_ashrrev_i32_e32 v27, 31, v26
	v_lshlrev_b32_e32 v4, 6, v2
	v_cmp_gt_u32_e64 s[46:47], 64, v148
	v_lshl_or_b32 v130, v164, 3, v163
	v_lshlrev_b32_e32 v130, 2, v130
	s_nop 0
	v_readfirstlane_b32 s100, v130
	s_nop 4
	s_load_dword s101, s[82:83], s100
	s_load_dword s100, s[80:81], s100
	v_mov_b32_e32 v130, 0
	v_mov_b32_e32 v166, 0
	s_and_saveexec_b64 s[0:1], s[46:47]
	s_cbranch_execz .LBB0_558
	v_xor_b32_e32 v0, 63, v148
	v_ashrrev_i32_e32 v5, 31, v4
	v_cndmask_b32_e64 v0, v0, v148, s[44:45]
	v_lshl_add_u64 v[2:3], v[4:5], 0, v[26:27]
	v_or_b32_e32 v2, v2, v0
	v_readlane_b32 s22, v251, 58
	v_lshlrev_b64 v[2:3], 7, v[2:3]
	v_readlane_b32 s23, v251, 59
	v_lshlrev_b32_e32 v0, 5, v164
	s_nop 0
	v_lshl_add_u64 v[2:3], s[22:23], 0, v[2:3]
	v_lshl_add_u64 v[2:3], v[2:3], 0, v[0:1]
	v_lshlrev_b32_e32 v0, 2, v163
	v_lshl_add_u64 v[2:3], v[2:3], 0, v[0:1]
	global_load_dword v165, v[2:3], off
	global_load_dword v166, v[2:3], off offset:64
